# row phases: y (GEMM output) loads use default cache policy instead of nt
# baseline (speedup 1.0000x reference)
; DI float bflo(unsigned u) { return __uint_as_float(u << 16); }
; DI float bfhi(unsigned u) { return __uint_as_float(u & 0xffff0000u); }
; DI int lbid() { int b = blockIdx.x; asm volatile("" : "+s"(b)); return b; }
; DI void row_phase(const float* __restrict__ x_in, const u16* __restrict__ y, float c, const float* __restrict__ g_post,
;                   float* __restrict__ x_out, const float* __restrict__ g_pre, u16* __restrict__ hout) {
;     ...
;   for (int row = lbid() * 8 + wid; row < S; row += gridDim.x * 8) {
;     f32x4 xv[4];
; #pragma unroll
;     for (int i = 0; i < 4; ++i) xv[i] = __builtin_nontemporal_load((const f32x4*)(x_in + (size_t)row * DM + 4 * lane + 256 * i));
;     if (y) {
;       f32x4 yv[4];
;       float ss = 0.f;
; #pragma unroll
;       for (int i = 0; i < 4; ++i) {
;         typedef unsigned u32x2_t __attribute__((ext_vector_type(2)));
;         const u32x2_t yb = __builtin_nontemporal_load((const u32x2_t*)(y + (size_t)row * DM + 4 * lane + 256 * i));
;         yv[i] = f32x4{bflo(yb.x), bfhi(yb.x), bflo(yb.y), bfhi(yb.y)};
;         ss += yv[i][0] * yv[i][0] + yv[i][1] * yv[i][1] + yv[i][2] * yv[i][2] + yv[i][3] * yv[i][3];
;       }
;       ss = wave_sum(ss);
;       float r = c * rsqrtf(ss * (1.f / DM) + EPS);
; #pragma unroll
;       for (int i = 0; i < 4; ++i) {
;         f32x4 g = *(const f32x4*)(g_post + 4 * lane + 256 * i);
;         xv[i] += yv[i] * g * r;
.LBB0_114:
	v_ashrrev_i32_e32 v33, 31, v32
	v_lshlrev_b64 v[42:43], 11, v[32:33]
	v_lshl_add_u64 v[42:43], v[36:37], 0, v[42:43]
	global_load_dwordx2 v[68:69], v[42:43], off offset:512
	global_load_dwordx2 v[70:71], v[42:43], off
	global_load_dwordx2 v[72:73], v[42:43], off offset:1536
	global_load_dwordx2 v[74:75], v[42:43], off offset:1024
	v_lshlrev_b64 v[42:43], 12, v[32:33]
	v_lshl_add_u64 v[76:77], v[34:35], 0, v[42:43]
	global_load_dwordx4 v[52:55], v[76:77], off nt
	global_load_dwordx4 v[56:59], v[76:77], off offset:1024 nt
	global_load_dwordx4 v[60:63], v[76:77], off offset:2048 nt
	global_load_dwordx4 v[64:67], v[76:77], off offset:3072 nt
	v_lshl_add_u64 v[42:43], v[38:39], 0, v[42:43]
	s_waitcnt vmcnt(7)
	v_and_b32_e32 v79, 0xffff0000, v68
	s_waitcnt vmcnt(6)
	v_and_b32_e32 v78, 0xffff0000, v70
	v_lshlrev_b32_e32 v77, 16, v68
	v_lshlrev_b32_e32 v76, 16, v70
	v_lshlrev_b32_e32 v80, 16, v71
	v_and_b32_e32 v68, 0xffff0000, v71
	s_waitcnt vmcnt(5)
	v_lshlrev_b32_e32 v71, 16, v72
	s_waitcnt vmcnt(4)
	v_lshlrev_b32_e32 v70, 16, v74
	v_and_b32_e32 v83, 0xffff0000, v72
	v_and_b32_e32 v82, 0xffff0000, v74
	v_lshlrev_b32_e32 v84, 16, v75
	v_and_b32_e32 v72, 0xffff0000, v75
	v_pk_mul_f32 v[74:75], v[78:79], v[78:79]
	v_lshlrev_b32_e32 v81, 16, v69
	v_pk_mul_f32 v[86:87], v[82:83], v[82:83]
	v_pk_fma_f32 v[74:75], v[76:77], v[76:77], v[74:75]
	v_and_b32_e32 v69, 0xffff0000, v69
	v_lshlrev_b32_e32 v85, 16, v73
	v_pk_fma_f32 v[86:87], v[70:71], v[70:71], v[86:87]
	v_pk_fma_f32 v[74:75], v[80:81], v[80:81], v[74:75]
	v_and_b32_e32 v73, 0xffff0000, v73
	v_pk_fma_f32 v[86:87], v[84:85], v[84:85], v[86:87]
	v_pk_fma_f32 v[74:75], v[68:69], v[68:69], v[74:75]
	v_pk_fma_f32 v[86:87], v[72:73], v[72:73], v[86:87]
	v_add_f32_e32 v33, v74, v75
	v_add_f32_e32 v33, v33, v86
	v_add_f32_e32 v33, v33, v87
	ds_bpermute_b32 v51, v44, v33
	v_mov_b32_e32 v74, v76
	v_mov_b32_e32 v75, v78
	v_mov_b32_e32 v78, v77
	v_mov_b32_e32 v86, v80
	s_waitcnt lgkmcnt(0)
	v_add_f32_e32 v33, v33, v51
	ds_bpermute_b32 v51, v45, v33
	v_mov_b32_e32 v76, v70
	v_mov_b32_e32 v77, v82
	v_mov_b32_e32 v82, v71
	v_pk_mul_f32 v[70:71], v[8:9], v[74:75]
	s_waitcnt lgkmcnt(0)
	v_add_f32_e32 v33, v33, v51
	ds_bpermute_b32 v51, v46, v33
	v_pk_mul_f32 v[78:79], v[0:1], v[78:79]
	v_mov_b32_e32 v87, v68
	v_pk_mul_f32 v[76:77], v[4:5], v[76:77]
	v_pk_mul_f32 v[82:83], v[16:17], v[82:83]
	s_waitcnt lgkmcnt(0)
	v_add_f32_e32 v33, v33, v51
	ds_bpermute_b32 v51, v47, v33
	v_mov_b32_e32 v68, v81
	v_mov_b32_e32 v88, v84
	v_mov_b32_e32 v89, v72
	v_pk_mul_f32 v[74:75], v[10:11], v[86:87]
	s_waitcnt lgkmcnt(0)
	v_add_f32_e32 v33, v33, v51
	ds_bpermute_b32 v51, v48, v33
	v_mov_b32_e32 v72, v85
	v_pk_mul_f32 v[68:69], v[2:3], v[68:69]
	v_pk_mul_f32 v[86:87], v[6:7], v[88:89]
	v_pk_mul_f32 v[72:73], v[18:19], v[72:73]
	s_waitcnt lgkmcnt(0)
	v_add_f32_e32 v33, v33, v51
	ds_bpermute_b32 v51, v49, v33
	s_waitcnt lgkmcnt(0)
	v_add_f32_e32 v33, v33, v51
	v_fmamk_f32 v33, v33, 0x3a800000, v50
	v_mul_f32_e32 v51, 0x4b800000, v33
	v_cmp_gt_f32_e32 vcc, s5, v33
	s_nop 1
	v_cndmask_b32_e32 v33, v33, v51, vcc
	v_rsq_f32_e32 v33, v33
	s_nop 0
	v_mul_f32_e32 v51, 0x45800000, v33
	v_cndmask_b32_e32 v33, v33, v51, vcc
	v_mul_f32_e32 v80, 0.5, v33
	s_waitcnt vmcnt(3)
	v_pk_fma_f32 v[52:53], v[70:71], v[80:81], v[52:53] op_sel_hi:[1,0,1]
	s_waitcnt vmcnt(2)
	v_pk_fma_f32 v[56:57], v[78:79], v[80:81], v[56:57] op_sel_hi:[1,0,1]
	s_waitcnt vmcnt(1)
	v_pk_fma_f32 v[60:61], v[76:77], v[80:81], v[60:61] op_sel_hi:[1,0,1]
	s_waitcnt vmcnt(0)
; DI void row_phase(const float* __restrict__ x_in, const u16* __restrict__ y, float c, const float* __restrict__ g_post,
;                   float* __restrict__ x_out, const float* __restrict__ g_pre, u16* __restrict__ hout) {
;     ...
;       ss = wave_sum(ss);
;       float r = c * rsqrtf(ss * (1.f / DM) + EPS);
; #pragma unroll
;       for (int i = 0; i < 4; ++i) {
;         f32x4 g = *(const f32x4*)(g_post + 4 * lane + 256 * i);
;         xv[i] += yv[i] * g * r;
;         __builtin_nontemporal_store(xv[i], (f32x4*)(x_out + (size_t)row * DM + 4 * lane + 256 * i));
;       }
;     }
;     if (g_pre) {
;       float ss = 0.f;
; #pragma unroll
;       for (int i = 0; i < 4; ++i) ss += xv[i][0] * xv[i][0] + xv[i][1] * xv[i][1] + xv[i][2] * xv[i][2] + xv[i][3] * xv[i][3];
;       ss = wave_sum(ss);
;       float r = rsqrtf(ss * (1.f / DM) + EPS);
; #pragma unroll
;       for (int i = 0; i < 4; ++i) {
;         f32x4 g = *(const f32x4*)(g_pre + 4 * lane + 256 * i);
;         f32x4 hv = xv[i] * g * r;
;         uint2 o = {pack2(hv[0], hv[1]), pack2(hv[2], hv[3])};
;         *(uint2*)(hout + (size_t)row * LDH + 4 * lane + 256 * i) = o;
;       }
	v_pk_fma_f32 v[64:65], v[82:83], v[80:81], v[64:65] op_sel_hi:[1,0,1]
	v_mov_b32_e32 v70, v53
	v_mov_b32_e32 v71, v57
	v_pk_fma_f32 v[54:55], v[74:75], v[80:81], v[54:55] op_sel_hi:[1,0,1]
	v_pk_fma_f32 v[58:59], v[68:69], v[80:81], v[58:59] op_sel_hi:[1,0,1]
	v_mov_b32_e32 v68, v52
	v_mov_b32_e32 v69, v56
	v_mov_b32_e32 v78, v65
	v_mov_b32_e32 v79, v61
	v_pk_mul_f32 v[70:71], v[70:71], v[70:71]
	v_pk_fma_f32 v[62:63], v[86:87], v[80:81], v[62:63] op_sel_hi:[1,0,1]
	v_pk_fma_f32 v[66:67], v[72:73], v[80:81], v[66:67] op_sel_hi:[1,0,1]
	v_mov_b32_e32 v72, v54
	v_mov_b32_e32 v73, v58
	v_mov_b32_e32 v76, v64
	v_mov_b32_e32 v77, v60
	v_pk_mul_f32 v[78:79], v[78:79], v[78:79]
	v_pk_fma_f32 v[68:69], v[68:69], v[68:69], v[70:71]
	v_mov_b32_e32 v74, v55
	v_mov_b32_e32 v75, v59
	v_mov_b32_e32 v80, v66
	v_mov_b32_e32 v81, v62
	v_pk_fma_f32 v[70:71], v[76:77], v[76:77], v[78:79]
	v_pk_fma_f32 v[68:69], v[72:73], v[72:73], v[68:69]
	v_mov_b32_e32 v82, v67
	v_mov_b32_e32 v83, v63
	v_pk_fma_f32 v[70:71], v[80:81], v[80:81], v[70:71]
	v_pk_fma_f32 v[68:69], v[74:75], v[74:75], v[68:69]
	v_pk_fma_f32 v[70:71], v[82:83], v[82:83], v[70:71]
	v_add_f32_e32 v33, v68, v69
	v_add_f32_e32 v33, v71, v33
	v_add_f32_e32 v33, v70, v33
	ds_bpermute_b32 v51, v44, v33
	v_mad_i64_i32 v[68:69], s[16:17], v32, s6, v[40:41]
	v_add_u32_e32 v32, s4, v32
	v_cmp_lt_i32_e32 vcc, s7, v32
	s_waitcnt lgkmcnt(0)
	v_add_f32_e32 v33, v33, v51
	ds_bpermute_b32 v51, v45, v33
	s_or_b64 s[2:3], vcc, s[2:3]
	global_store_dwordx4 v[42:43], v[52:55], off nt
	global_store_dwordx4 v[42:43], v[56:59], off offset:1024 nt
	global_store_dwordx4 v[42:43], v[60:63], off offset:2048 nt
	global_store_dwordx4 v[42:43], v[64:67], off offset:3072 nt
	v_pk_mul_f32 v[42:43], v[12:13], v[52:53]
	s_waitcnt lgkmcnt(0)
	v_add_f32_e32 v33, v33, v51
	ds_bpermute_b32 v51, v46, v33
	v_pk_mul_f32 v[52:53], v[14:15], v[54:55]
	v_pk_mul_f32 v[54:55], v[20:21], v[56:57]
	v_pk_mul_f32 v[56:57], v[22:23], v[58:59]
	v_pk_mul_f32 v[58:59], v[24:25], v[60:61]
	s_waitcnt lgkmcnt(0)
	v_add_f32_e32 v33, v33, v51
	ds_bpermute_b32 v51, v47, v33
	v_pk_mul_f32 v[60:61], v[26:27], v[62:63]
	v_pk_mul_f32 v[62:63], v[28:29], v[64:65]
	v_pk_mul_f32 v[64:65], v[30:31], v[66:67]
	s_waitcnt lgkmcnt(0)
	v_add_f32_e32 v33, v33, v51
	ds_bpermute_b32 v51, v48, v33
	s_waitcnt lgkmcnt(0)
	v_add_f32_e32 v33, v33, v51
	ds_bpermute_b32 v51, v49, v33
	s_waitcnt lgkmcnt(0)
	v_add_f32_e32 v33, v33, v51
	v_fmamk_f32 v33, v33, 0x3a800000, v50
	v_mul_f32_e32 v51, 0x4b800000, v33
	v_cmp_gt_f32_e32 vcc, s5, v33
	s_nop 1
	v_cndmask_b32_e32 v33, v33, v51, vcc
	v_rsq_f32_e32 v33, v33
	s_nop 0
	v_mul_f32_e32 v51, 0x45800000, v33
	v_cndmask_b32_e32 v66, v33, v51, vcc
	v_pk_mul_f32 v[52:53], v[52:53], v[66:67] op_sel_hi:[1,0]
	v_pk_mul_f32 v[42:43], v[42:43], v[66:67] op_sel_hi:[1,0]
	v_pk_mul_f32 v[56:57], v[56:57], v[66:67] op_sel_hi:[1,0]
	v_pk_mul_f32 v[54:55], v[54:55], v[66:67] op_sel_hi:[1,0]
	v_pk_mul_f32 v[60:61], v[60:61], v[66:67] op_sel_hi:[1,0]
	v_pk_mul_f32 v[58:59], v[58:59], v[66:67] op_sel_hi:[1,0]
	v_pk_mul_f32 v[64:65], v[64:65], v[66:67] op_sel_hi:[1,0]
	v_pk_mul_f32 v[62:63], v[62:63], v[66:67] op_sel_hi:[1,0]
	v_cvt_pk_bf16_f32 v42, v42, v43
	v_cvt_pk_bf16_f32 v43, v52, v53
	v_cvt_pk_bf16_f32 v52, v54, v55
	v_cvt_pk_bf16_f32 v53, v56, v57
	v_cvt_pk_bf16_f32 v54, v58, v59
	v_cvt_pk_bf16_f32 v55, v60, v61
	v_cvt_pk_bf16_f32 v56, v62, v63
	v_cvt_pk_bf16_f32 v57, v64, v65
	global_store_dwordx2 v[68:69], v[42:43], off
	global_store_dwordx2 v[68:69], v[52:53], off offset:512
	global_store_dwordx2 v[68:69], v[54:55], off offset:1024
	global_store_dwordx2 v[68:69], v[56:57], off offset:1536
	s_andn2_b64 exec, exec, s[2:3]
	s_cbranch_execnz .LBB0_114

; DI float bflo(unsigned u) { return __uint_as_float(u << 16); }
; DI float bfhi(unsigned u) { return __uint_as_float(u & 0xffff0000u); }
; DI int lbid() { int b = blockIdx.x; asm volatile("" : "+s"(b)); return b; }
; DI void row_phase(const float* __restrict__ x_in, const u16* __restrict__ y, float c, const float* __restrict__ g_post,
;                   float* __restrict__ x_out, const float* __restrict__ g_pre, u16* __restrict__ hout) {
;     ...
;   for (int row = lbid() * 8 + wid; row < S; row += gridDim.x * 8) {
;     f32x4 xv[4];
; #pragma unroll
;     for (int i = 0; i < 4; ++i) xv[i] = __builtin_nontemporal_load((const f32x4*)(x_in + (size_t)row * DM + 4 * lane + 256 * i));
;     if (y) {
;       f32x4 yv[4];
;       float ss = 0.f;
; #pragma unroll
;       for (int i = 0; i < 4; ++i) {
;         typedef unsigned u32x2_t __attribute__((ext_vector_type(2)));
;         const u32x2_t yb = __builtin_nontemporal_load((const u32x2_t*)(y + (size_t)row * DM + 4 * lane + 256 * i));
;         yv[i] = f32x4{bflo(yb.x), bfhi(yb.x), bflo(yb.y), bfhi(yb.y)};
;         ss += yv[i][0] * yv[i][0] + yv[i][1] * yv[i][1] + yv[i][2] * yv[i][2] + yv[i][3] * yv[i][3];
;       }
;       ss = wave_sum(ss);
;       float r = c * rsqrtf(ss * (1.f / DM) + EPS);
; #pragma unroll
;       for (int i = 0; i < 4; ++i) {
;         f32x4 g = *(const f32x4*)(g_post + 4 * lane + 256 * i);
;         xv[i] += yv[i] * g * r;
.LBB0_329:
	v_ashrrev_i32_e32 v33, 31, v32
	v_lshlrev_b64 v[40:41], 11, v[32:33]
	v_lshl_add_u64 v[40:41], v[36:37], 0, v[40:41]
	global_load_dwordx2 v[60:61], v[40:41], off offset:512
	global_load_dwordx2 v[62:63], v[40:41], off
	global_load_dwordx2 v[64:65], v[40:41], off offset:1536
	global_load_dwordx2 v[66:67], v[40:41], off offset:1024
	v_lshlrev_b64 v[40:41], 12, v[32:33]
	v_lshl_add_u64 v[40:41], v[34:35], 0, v[40:41]
	global_load_dwordx4 v[44:47], v[40:41], off nt
	global_load_dwordx4 v[48:51], v[40:41], off offset:1024 nt
	global_load_dwordx4 v[52:55], v[40:41], off offset:2048 nt
	global_load_dwordx4 v[56:59], v[40:41], off offset:3072 nt
	s_waitcnt vmcnt(7)
	v_and_b32_e32 v71, 0xffff0000, v60
	s_waitcnt vmcnt(6)
	v_and_b32_e32 v70, 0xffff0000, v62
	v_lshlrev_b32_e32 v69, 16, v60
	v_lshlrev_b32_e32 v68, 16, v62
	v_lshlrev_b32_e32 v72, 16, v63
	v_and_b32_e32 v60, 0xffff0000, v63
	s_waitcnt vmcnt(5)
	v_lshlrev_b32_e32 v63, 16, v64
	s_waitcnt vmcnt(4)
	v_lshlrev_b32_e32 v62, 16, v66
	v_and_b32_e32 v75, 0xffff0000, v64
	v_and_b32_e32 v74, 0xffff0000, v66
	v_lshlrev_b32_e32 v76, 16, v67
	v_and_b32_e32 v64, 0xffff0000, v67
	v_pk_mul_f32 v[66:67], v[70:71], v[70:71]
	v_lshlrev_b32_e32 v73, 16, v61
	v_pk_mul_f32 v[78:79], v[74:75], v[74:75]
	v_pk_fma_f32 v[66:67], v[68:69], v[68:69], v[66:67]
	v_and_b32_e32 v61, 0xffff0000, v61
	v_lshlrev_b32_e32 v77, 16, v65
	v_pk_fma_f32 v[78:79], v[62:63], v[62:63], v[78:79]
	v_pk_fma_f32 v[66:67], v[72:73], v[72:73], v[66:67]
	v_and_b32_e32 v65, 0xffff0000, v65
	v_pk_fma_f32 v[78:79], v[76:77], v[76:77], v[78:79]
	v_pk_fma_f32 v[66:67], v[60:61], v[60:61], v[66:67]
	v_pk_fma_f32 v[78:79], v[64:65], v[64:65], v[78:79]
	v_add_f32_e32 v33, v66, v67
	v_add_f32_e32 v33, v33, v78
	v_add_f32_e32 v33, v33, v79
	ds_bpermute_b32 v43, v159, v33
	v_mov_b32_e32 v66, v68
	v_mov_b32_e32 v67, v70
	v_mov_b32_e32 v70, v69
	v_mov_b32_e32 v78, v72
	s_waitcnt lgkmcnt(0)
	v_add_f32_e32 v33, v33, v43
	ds_bpermute_b32 v43, v160, v33
	v_mov_b32_e32 v68, v62
	v_mov_b32_e32 v69, v74
	v_mov_b32_e32 v74, v63
	v_pk_mul_f32 v[62:63], v[8:9], v[66:67]
	s_waitcnt lgkmcnt(0)
	v_add_f32_e32 v33, v33, v43
	ds_bpermute_b32 v43, v161, v33
	v_pk_mul_f32 v[70:71], v[0:1], v[70:71]
	v_mov_b32_e32 v79, v60
	v_pk_mul_f32 v[68:69], v[4:5], v[68:69]
	v_pk_mul_f32 v[74:75], v[16:17], v[74:75]
	s_waitcnt lgkmcnt(0)
	v_add_f32_e32 v33, v33, v43
	ds_bpermute_b32 v43, v162, v33
	v_mov_b32_e32 v60, v73
	v_mov_b32_e32 v80, v76
	v_mov_b32_e32 v81, v64
	v_pk_mul_f32 v[66:67], v[10:11], v[78:79]
	s_waitcnt lgkmcnt(0)
	v_add_f32_e32 v33, v33, v43
	ds_bpermute_b32 v43, v163, v33
	v_mov_b32_e32 v64, v77
	v_pk_mul_f32 v[60:61], v[2:3], v[60:61]
	v_pk_mul_f32 v[78:79], v[6:7], v[80:81]
	v_pk_mul_f32 v[64:65], v[18:19], v[64:65]
	s_waitcnt lgkmcnt(0)
	v_add_f32_e32 v33, v33, v43
	ds_bpermute_b32 v43, v164, v33
	s_waitcnt lgkmcnt(0)
	v_add_f32_e32 v33, v33, v43
	v_fmamk_f32 v33, v33, 0x3a800000, v42
	v_mul_f32_e32 v43, 0x4b800000, v33
	v_cmp_gt_f32_e32 vcc, s5, v33
	s_nop 1
	v_cndmask_b32_e32 v33, v33, v43, vcc
	v_rsq_f32_e32 v33, v33
	s_nop 0
	v_mul_f32_e32 v43, 0x45800000, v33
	v_cndmask_b32_e32 v72, v33, v43, vcc
	s_waitcnt vmcnt(3)
	v_pk_fma_f32 v[44:45], v[62:63], v[72:73], v[44:45] op_sel_hi:[1,0,1]
	s_waitcnt vmcnt(2)
	v_pk_fma_f32 v[48:49], v[70:71], v[72:73], v[48:49] op_sel_hi:[1,0,1]
	s_waitcnt vmcnt(1)
	v_pk_fma_f32 v[52:53], v[68:69], v[72:73], v[52:53] op_sel_hi:[1,0,1]
	s_waitcnt vmcnt(0)
; DI void row_phase(const float* __restrict__ x_in, const u16* __restrict__ y, float c, const float* __restrict__ g_post,
;                   float* __restrict__ x_out, const float* __restrict__ g_pre, u16* __restrict__ hout) {
;     ...
;       ss = wave_sum(ss);
;       float r = c * rsqrtf(ss * (1.f / DM) + EPS);
; #pragma unroll
;       for (int i = 0; i < 4; ++i) {
;         f32x4 g = *(const f32x4*)(g_post + 4 * lane + 256 * i);
;         xv[i] += yv[i] * g * r;
;         __builtin_nontemporal_store(xv[i], (f32x4*)(x_out + (size_t)row * DM + 4 * lane + 256 * i));
;       }
;     }
;     if (g_pre) {
;       float ss = 0.f;
; #pragma unroll
;       for (int i = 0; i < 4; ++i) ss += xv[i][0] * xv[i][0] + xv[i][1] * xv[i][1] + xv[i][2] * xv[i][2] + xv[i][3] * xv[i][3];
;       ss = wave_sum(ss);
;       float r = rsqrtf(ss * (1.f / DM) + EPS);
; #pragma unroll
;       for (int i = 0; i < 4; ++i) {
;         f32x4 g = *(const f32x4*)(g_pre + 4 * lane + 256 * i);
;         f32x4 hv = xv[i] * g * r;
;         uint2 o = {pack2(hv[0], hv[1]), pack2(hv[2], hv[3])};
;         *(uint2*)(hout + (size_t)row * LDH + 4 * lane + 256 * i) = o;
;       }
	v_pk_fma_f32 v[56:57], v[74:75], v[72:73], v[56:57] op_sel_hi:[1,0,1]
	v_mov_b32_e32 v62, v45
	v_mov_b32_e32 v63, v49
	v_pk_fma_f32 v[46:47], v[66:67], v[72:73], v[46:47] op_sel_hi:[1,0,1]
	v_pk_fma_f32 v[50:51], v[60:61], v[72:73], v[50:51] op_sel_hi:[1,0,1]
	v_mov_b32_e32 v60, v44
	v_mov_b32_e32 v61, v48
	v_mov_b32_e32 v70, v57
	v_mov_b32_e32 v71, v53
	v_pk_mul_f32 v[62:63], v[62:63], v[62:63]
	v_pk_fma_f32 v[54:55], v[78:79], v[72:73], v[54:55] op_sel_hi:[1,0,1]
	v_pk_fma_f32 v[58:59], v[64:65], v[72:73], v[58:59] op_sel_hi:[1,0,1]
	v_mov_b32_e32 v64, v46
	v_mov_b32_e32 v65, v50
	v_mov_b32_e32 v68, v56
	v_mov_b32_e32 v69, v52
	v_pk_mul_f32 v[70:71], v[70:71], v[70:71]
	v_pk_fma_f32 v[60:61], v[60:61], v[60:61], v[62:63]
	v_mov_b32_e32 v66, v47
	v_mov_b32_e32 v67, v51
	v_mov_b32_e32 v72, v58
	v_mov_b32_e32 v73, v54
	v_pk_fma_f32 v[62:63], v[68:69], v[68:69], v[70:71]
	v_pk_fma_f32 v[60:61], v[64:65], v[64:65], v[60:61]
	v_mov_b32_e32 v74, v59
	v_mov_b32_e32 v75, v55
	v_pk_fma_f32 v[62:63], v[72:73], v[72:73], v[62:63]
	v_pk_fma_f32 v[60:61], v[66:67], v[66:67], v[60:61]
	v_pk_fma_f32 v[62:63], v[74:75], v[74:75], v[62:63]
	v_add_f32_e32 v33, v60, v61
	v_add_f32_e32 v33, v63, v33
	v_add_f32_e32 v33, v62, v33
	ds_bpermute_b32 v43, v159, v33
	v_mad_i64_i32 v[60:61], s[34:35], v32, s6, v[38:39]
	v_add_u32_e32 v32, s4, v32
	v_cmp_lt_i32_e32 vcc, s7, v32
	s_waitcnt lgkmcnt(0)
	v_add_f32_e32 v33, v33, v43
	ds_bpermute_b32 v43, v160, v33
	s_or_b64 s[2:3], vcc, s[2:3]
	global_store_dwordx4 v[40:41], v[44:47], off nt
	global_store_dwordx4 v[40:41], v[48:51], off offset:1024 nt
	global_store_dwordx4 v[40:41], v[52:55], off offset:2048 nt
	global_store_dwordx4 v[40:41], v[56:59], off offset:3072 nt
	v_pk_mul_f32 v[40:41], v[12:13], v[44:45]
	s_waitcnt lgkmcnt(0)
	v_add_f32_e32 v33, v33, v43
	ds_bpermute_b32 v43, v161, v33
	v_pk_mul_f32 v[44:45], v[14:15], v[46:47]
	v_pk_mul_f32 v[46:47], v[20:21], v[48:49]
	v_pk_mul_f32 v[48:49], v[22:23], v[50:51]
	v_pk_mul_f32 v[50:51], v[24:25], v[52:53]
	s_waitcnt lgkmcnt(0)
	v_add_f32_e32 v33, v33, v43
	ds_bpermute_b32 v43, v162, v33
	v_pk_mul_f32 v[52:53], v[26:27], v[54:55]
	v_pk_mul_f32 v[54:55], v[28:29], v[56:57]
	v_pk_mul_f32 v[56:57], v[30:31], v[58:59]
	s_waitcnt lgkmcnt(0)
	v_add_f32_e32 v33, v33, v43
	ds_bpermute_b32 v43, v163, v33
	s_waitcnt lgkmcnt(0)
	v_add_f32_e32 v33, v33, v43
	ds_bpermute_b32 v43, v164, v33
	s_waitcnt lgkmcnt(0)
	v_add_f32_e32 v33, v33, v43
	v_fmamk_f32 v33, v33, 0x3a800000, v42
	v_mul_f32_e32 v43, 0x4b800000, v33
	v_cmp_gt_f32_e32 vcc, s5, v33
	s_nop 1
	v_cndmask_b32_e32 v33, v33, v43, vcc
	v_rsq_f32_e32 v33, v33
	s_nop 0
	v_mul_f32_e32 v43, 0x45800000, v33
	v_cndmask_b32_e32 v58, v33, v43, vcc
	v_pk_mul_f32 v[44:45], v[44:45], v[58:59] op_sel_hi:[1,0]
	v_pk_mul_f32 v[40:41], v[40:41], v[58:59] op_sel_hi:[1,0]
	v_pk_mul_f32 v[48:49], v[48:49], v[58:59] op_sel_hi:[1,0]
	v_pk_mul_f32 v[46:47], v[46:47], v[58:59] op_sel_hi:[1,0]
	v_pk_mul_f32 v[52:53], v[52:53], v[58:59] op_sel_hi:[1,0]
	v_pk_mul_f32 v[50:51], v[50:51], v[58:59] op_sel_hi:[1,0]
	v_pk_mul_f32 v[56:57], v[56:57], v[58:59] op_sel_hi:[1,0]
	v_pk_mul_f32 v[54:55], v[54:55], v[58:59] op_sel_hi:[1,0]
	v_cvt_pk_bf16_f32 v40, v40, v41
	v_cvt_pk_bf16_f32 v41, v44, v45
	v_cvt_pk_bf16_f32 v44, v46, v47
	v_cvt_pk_bf16_f32 v45, v48, v49
	v_cvt_pk_bf16_f32 v46, v50, v51
	v_cvt_pk_bf16_f32 v47, v52, v53
	v_cvt_pk_bf16_f32 v48, v54, v55
	v_cvt_pk_bf16_f32 v49, v56, v57
	global_store_dwordx2 v[60:61], v[40:41], off
	global_store_dwordx2 v[60:61], v[44:45], off offset:512
	global_store_dwordx2 v[60:61], v[46:47], off offset:1024
	global_store_dwordx2 v[60:61], v[48:49], off offset:1536
	s_andn2_b64 exec, exec, s[2:3]
	s_cbranch_execnz .LBB0_329

; DI float bflo(unsigned u) { return __uint_as_float(u << 16); }
; DI float bfhi(unsigned u) { return __uint_as_float(u & 0xffff0000u); }
; DI int lbid() { int b = blockIdx.x; asm volatile("" : "+s"(b)); return b; }
; DI void row_phase(const float* __restrict__ x_in, const u16* __restrict__ y, float c, const float* __restrict__ g_post,
;                   float* __restrict__ x_out, const float* __restrict__ g_pre, u16* __restrict__ hout) {
;     ...
;   for (int row = lbid() * 8 + wid; row < S; row += gridDim.x * 8) {
;     f32x4 xv[4];
; #pragma unroll
;     for (int i = 0; i < 4; ++i) xv[i] = __builtin_nontemporal_load((const f32x4*)(x_in + (size_t)row * DM + 4 * lane + 256 * i));
;     if (y) {
;       f32x4 yv[4];
;       float ss = 0.f;
; #pragma unroll
;       for (int i = 0; i < 4; ++i) {
;         typedef unsigned u32x2_t __attribute__((ext_vector_type(2)));
;         const u32x2_t yb = __builtin_nontemporal_load((const u32x2_t*)(y + (size_t)row * DM + 4 * lane + 256 * i));
;         yv[i] = f32x4{bflo(yb.x), bfhi(yb.x), bflo(yb.y), bfhi(yb.y)};
;         ss += yv[i][0] * yv[i][0] + yv[i][1] * yv[i][1] + yv[i][2] * yv[i][2] + yv[i][3] * yv[i][3];
;       }
;       ss = wave_sum(ss);
;       float r = c * rsqrtf(ss * (1.f / DM) + EPS);
; #pragma unroll
;       for (int i = 0; i < 4; ++i) {
;         f32x4 g = *(const f32x4*)(g_post + 4 * lane + 256 * i);
;         xv[i] += yv[i] * g * r;
.LBB0_402:
	v_ashrrev_i32_e32 v33, 31, v32
	v_lshlrev_b64 v[40:41], 11, v[32:33]
	v_lshl_add_u64 v[40:41], v[36:37], 0, v[40:41]
	global_load_dwordx2 v[60:61], v[40:41], off offset:512
	global_load_dwordx2 v[62:63], v[40:41], off
	global_load_dwordx2 v[64:65], v[40:41], off offset:1536
	global_load_dwordx2 v[66:67], v[40:41], off offset:1024
	v_lshlrev_b64 v[40:41], 12, v[32:33]
	v_lshl_add_u64 v[40:41], v[34:35], 0, v[40:41]
	global_load_dwordx4 v[44:47], v[40:41], off nt
	global_load_dwordx4 v[48:51], v[40:41], off offset:1024 nt
	global_load_dwordx4 v[52:55], v[40:41], off offset:2048 nt
	global_load_dwordx4 v[56:59], v[40:41], off offset:3072 nt
	s_waitcnt vmcnt(7)
	v_and_b32_e32 v71, 0xffff0000, v60
	s_waitcnt vmcnt(6)
	v_and_b32_e32 v70, 0xffff0000, v62
	v_lshlrev_b32_e32 v69, 16, v60
	v_lshlrev_b32_e32 v68, 16, v62
	v_lshlrev_b32_e32 v72, 16, v63
	v_and_b32_e32 v60, 0xffff0000, v63
	s_waitcnt vmcnt(5)
	v_lshlrev_b32_e32 v63, 16, v64
	s_waitcnt vmcnt(4)
	v_lshlrev_b32_e32 v62, 16, v66
	v_and_b32_e32 v75, 0xffff0000, v64
	v_and_b32_e32 v74, 0xffff0000, v66
	v_lshlrev_b32_e32 v76, 16, v67
	v_and_b32_e32 v64, 0xffff0000, v67
	v_pk_mul_f32 v[66:67], v[70:71], v[70:71]
	v_lshlrev_b32_e32 v73, 16, v61
	v_pk_mul_f32 v[78:79], v[74:75], v[74:75]
	v_pk_fma_f32 v[66:67], v[68:69], v[68:69], v[66:67]
	v_and_b32_e32 v61, 0xffff0000, v61
	v_lshlrev_b32_e32 v77, 16, v65
	v_pk_fma_f32 v[78:79], v[62:63], v[62:63], v[78:79]
	v_pk_fma_f32 v[66:67], v[72:73], v[72:73], v[66:67]
	v_and_b32_e32 v65, 0xffff0000, v65
	v_pk_fma_f32 v[78:79], v[76:77], v[76:77], v[78:79]
	v_pk_fma_f32 v[66:67], v[60:61], v[60:61], v[66:67]
	v_pk_fma_f32 v[78:79], v[64:65], v[64:65], v[78:79]
	v_add_f32_e32 v33, v66, v67
	v_add_f32_e32 v33, v33, v78
	v_add_f32_e32 v33, v33, v79
	ds_bpermute_b32 v43, v159, v33
	v_mov_b32_e32 v66, v68
	v_mov_b32_e32 v67, v70
	v_mov_b32_e32 v70, v69
	v_mov_b32_e32 v78, v72
	s_waitcnt lgkmcnt(0)
	v_add_f32_e32 v33, v33, v43
	ds_bpermute_b32 v43, v160, v33
	v_mov_b32_e32 v68, v62
	v_mov_b32_e32 v69, v74
	v_mov_b32_e32 v74, v63
	v_pk_mul_f32 v[62:63], v[8:9], v[66:67]
	s_waitcnt lgkmcnt(0)
	v_add_f32_e32 v33, v33, v43
	ds_bpermute_b32 v43, v161, v33
	v_pk_mul_f32 v[70:71], v[0:1], v[70:71]
	v_mov_b32_e32 v79, v60
	v_pk_mul_f32 v[68:69], v[4:5], v[68:69]
	v_pk_mul_f32 v[74:75], v[16:17], v[74:75]
	s_waitcnt lgkmcnt(0)
	v_add_f32_e32 v33, v33, v43
	ds_bpermute_b32 v43, v162, v33
	v_mov_b32_e32 v60, v73
	v_mov_b32_e32 v80, v76
	v_mov_b32_e32 v81, v64
	v_pk_mul_f32 v[66:67], v[10:11], v[78:79]
	s_waitcnt lgkmcnt(0)
	v_add_f32_e32 v33, v33, v43
	ds_bpermute_b32 v43, v163, v33
	v_mov_b32_e32 v64, v77
	v_pk_mul_f32 v[60:61], v[2:3], v[60:61]
	v_pk_mul_f32 v[78:79], v[6:7], v[80:81]
	v_pk_mul_f32 v[64:65], v[18:19], v[64:65]
	s_waitcnt lgkmcnt(0)
	v_add_f32_e32 v33, v33, v43
	ds_bpermute_b32 v43, v164, v33
	s_waitcnt lgkmcnt(0)
	v_add_f32_e32 v33, v33, v43
	v_fmamk_f32 v33, v33, 0x3a800000, v42
	v_mul_f32_e32 v43, 0x4b800000, v33
	v_cmp_gt_f32_e32 vcc, s5, v33
	s_nop 1
	v_cndmask_b32_e32 v33, v33, v43, vcc
	v_rsq_f32_e32 v33, v33
	s_nop 0
	v_mul_f32_e32 v43, 0x45800000, v33
	v_cndmask_b32_e32 v33, v33, v43, vcc
	v_mul_f32_e32 v72, 0.5, v33
	s_waitcnt vmcnt(3)
	v_pk_fma_f32 v[44:45], v[62:63], v[72:73], v[44:45] op_sel_hi:[1,0,1]
	s_waitcnt vmcnt(2)
	v_pk_fma_f32 v[48:49], v[70:71], v[72:73], v[48:49] op_sel_hi:[1,0,1]
	s_waitcnt vmcnt(1)
	v_pk_fma_f32 v[52:53], v[68:69], v[72:73], v[52:53] op_sel_hi:[1,0,1]
	s_waitcnt vmcnt(0)
; DI void row_phase(const float* __restrict__ x_in, const u16* __restrict__ y, float c, const float* __restrict__ g_post,
;                   float* __restrict__ x_out, const float* __restrict__ g_pre, u16* __restrict__ hout) {
;     ...
;       ss = wave_sum(ss);
;       float r = c * rsqrtf(ss * (1.f / DM) + EPS);
; #pragma unroll
;       for (int i = 0; i < 4; ++i) {
;         f32x4 g = *(const f32x4*)(g_post + 4 * lane + 256 * i);
;         xv[i] += yv[i] * g * r;
;         __builtin_nontemporal_store(xv[i], (f32x4*)(x_out + (size_t)row * DM + 4 * lane + 256 * i));
;       }
;     }
;     if (g_pre) {
;       float ss = 0.f;
; #pragma unroll
;       for (int i = 0; i < 4; ++i) ss += xv[i][0] * xv[i][0] + xv[i][1] * xv[i][1] + xv[i][2] * xv[i][2] + xv[i][3] * xv[i][3];
;       ss = wave_sum(ss);
;       float r = rsqrtf(ss * (1.f / DM) + EPS);
; #pragma unroll
;       for (int i = 0; i < 4; ++i) {
;         f32x4 g = *(const f32x4*)(g_pre + 4 * lane + 256 * i);
;         f32x4 hv = xv[i] * g * r;
;         uint2 o = {pack2(hv[0], hv[1]), pack2(hv[2], hv[3])};
;         *(uint2*)(hout + (size_t)row * LDH + 4 * lane + 256 * i) = o;
;       }
	v_pk_fma_f32 v[56:57], v[74:75], v[72:73], v[56:57] op_sel_hi:[1,0,1]
	v_mov_b32_e32 v62, v45
	v_mov_b32_e32 v63, v49
	v_pk_fma_f32 v[46:47], v[66:67], v[72:73], v[46:47] op_sel_hi:[1,0,1]
	v_pk_fma_f32 v[50:51], v[60:61], v[72:73], v[50:51] op_sel_hi:[1,0,1]
	v_mov_b32_e32 v60, v44
	v_mov_b32_e32 v61, v48
	v_mov_b32_e32 v70, v57
	v_mov_b32_e32 v71, v53
	v_pk_mul_f32 v[62:63], v[62:63], v[62:63]
	v_pk_fma_f32 v[54:55], v[78:79], v[72:73], v[54:55] op_sel_hi:[1,0,1]
	v_pk_fma_f32 v[58:59], v[64:65], v[72:73], v[58:59] op_sel_hi:[1,0,1]
	v_mov_b32_e32 v64, v46
	v_mov_b32_e32 v65, v50
	v_mov_b32_e32 v68, v56
	v_mov_b32_e32 v69, v52
	v_pk_mul_f32 v[70:71], v[70:71], v[70:71]
	v_pk_fma_f32 v[60:61], v[60:61], v[60:61], v[62:63]
	v_mov_b32_e32 v66, v47
	v_mov_b32_e32 v67, v51
	v_mov_b32_e32 v72, v58
	v_mov_b32_e32 v73, v54
	v_pk_fma_f32 v[62:63], v[68:69], v[68:69], v[70:71]
	v_pk_fma_f32 v[60:61], v[64:65], v[64:65], v[60:61]
	v_mov_b32_e32 v74, v59
	v_mov_b32_e32 v75, v55
	v_pk_fma_f32 v[62:63], v[72:73], v[72:73], v[62:63]
	v_pk_fma_f32 v[60:61], v[66:67], v[66:67], v[60:61]
	v_pk_fma_f32 v[62:63], v[74:75], v[74:75], v[62:63]
	v_add_f32_e32 v33, v60, v61
	v_add_f32_e32 v33, v63, v33
	v_add_f32_e32 v33, v62, v33
	ds_bpermute_b32 v43, v159, v33
	v_mad_i64_i32 v[60:61], s[34:35], v32, s6, v[38:39]
	v_add_u32_e32 v32, s4, v32
	v_cmp_lt_i32_e32 vcc, s7, v32
	s_waitcnt lgkmcnt(0)
	v_add_f32_e32 v33, v33, v43
	ds_bpermute_b32 v43, v160, v33
	s_or_b64 s[2:3], vcc, s[2:3]
	global_store_dwordx4 v[40:41], v[44:47], off nt
	global_store_dwordx4 v[40:41], v[48:51], off offset:1024 nt
	global_store_dwordx4 v[40:41], v[52:55], off offset:2048 nt
	global_store_dwordx4 v[40:41], v[56:59], off offset:3072 nt
	v_pk_mul_f32 v[40:41], v[12:13], v[44:45]
	s_waitcnt lgkmcnt(0)
	v_add_f32_e32 v33, v33, v43
	ds_bpermute_b32 v43, v161, v33
	v_pk_mul_f32 v[44:45], v[14:15], v[46:47]
	v_pk_mul_f32 v[46:47], v[20:21], v[48:49]
	v_pk_mul_f32 v[48:49], v[22:23], v[50:51]
	v_pk_mul_f32 v[50:51], v[24:25], v[52:53]
	s_waitcnt lgkmcnt(0)
	v_add_f32_e32 v33, v33, v43
	ds_bpermute_b32 v43, v162, v33
	v_pk_mul_f32 v[52:53], v[26:27], v[54:55]
	v_pk_mul_f32 v[54:55], v[28:29], v[56:57]
	v_pk_mul_f32 v[56:57], v[30:31], v[58:59]
	s_waitcnt lgkmcnt(0)
	v_add_f32_e32 v33, v33, v43
	ds_bpermute_b32 v43, v163, v33
	s_waitcnt lgkmcnt(0)
	v_add_f32_e32 v33, v33, v43
	ds_bpermute_b32 v43, v164, v33
	s_waitcnt lgkmcnt(0)
	v_add_f32_e32 v33, v33, v43
	v_fmamk_f32 v33, v33, 0x3a800000, v42
	v_mul_f32_e32 v43, 0x4b800000, v33
	v_cmp_gt_f32_e32 vcc, s5, v33
	s_nop 1
	v_cndmask_b32_e32 v33, v33, v43, vcc
	v_rsq_f32_e32 v33, v33
	s_nop 0
	v_mul_f32_e32 v43, 0x45800000, v33
	v_cndmask_b32_e32 v58, v33, v43, vcc
	v_pk_mul_f32 v[44:45], v[44:45], v[58:59] op_sel_hi:[1,0]
	v_pk_mul_f32 v[40:41], v[40:41], v[58:59] op_sel_hi:[1,0]
	v_pk_mul_f32 v[48:49], v[48:49], v[58:59] op_sel_hi:[1,0]
	v_pk_mul_f32 v[46:47], v[46:47], v[58:59] op_sel_hi:[1,0]
	v_pk_mul_f32 v[52:53], v[52:53], v[58:59] op_sel_hi:[1,0]
	v_pk_mul_f32 v[50:51], v[50:51], v[58:59] op_sel_hi:[1,0]
	v_pk_mul_f32 v[56:57], v[56:57], v[58:59] op_sel_hi:[1,0]
	v_pk_mul_f32 v[54:55], v[54:55], v[58:59] op_sel_hi:[1,0]
	v_cvt_pk_bf16_f32 v40, v40, v41
	v_cvt_pk_bf16_f32 v41, v44, v45
	v_cvt_pk_bf16_f32 v44, v46, v47
	v_cvt_pk_bf16_f32 v45, v48, v49
	v_cvt_pk_bf16_f32 v46, v50, v51
	v_cvt_pk_bf16_f32 v47, v52, v53
	v_cvt_pk_bf16_f32 v48, v54, v55
	v_cvt_pk_bf16_f32 v49, v56, v57
	global_store_dwordx2 v[60:61], v[40:41], off
	global_store_dwordx2 v[60:61], v[44:45], off offset:512
	global_store_dwordx2 v[60:61], v[46:47], off offset:1024
	global_store_dwordx2 v[60:61], v[48:49], off offset:1536
	s_andn2_b64 exec, exec, s[2:3]
	s_cbranch_execnz .LBB0_402

; DI float bflo(unsigned u) { return __uint_as_float(u << 16); }
; DI float bfhi(unsigned u) { return __uint_as_float(u & 0xffff0000u); }
; DI int lbid() { int b = blockIdx.x; asm volatile("" : "+s"(b)); return b; }
; DI void row_phase(const float* __restrict__ x_in, const u16* __restrict__ y, float c, const float* __restrict__ g_post,
;                   float* __restrict__ x_out, const float* __restrict__ g_pre, u16* __restrict__ hout) {
;     ...
;   for (int row = lbid() * 8 + wid; row < S; row += gridDim.x * 8) {
;     f32x4 xv[4];
; #pragma unroll
;     for (int i = 0; i < 4; ++i) xv[i] = __builtin_nontemporal_load((const f32x4*)(x_in + (size_t)row * DM + 4 * lane + 256 * i));
;     if (y) {
;       f32x4 yv[4];
;       float ss = 0.f;
; #pragma unroll
;       for (int i = 0; i < 4; ++i) {
;         typedef unsigned u32x2_t __attribute__((ext_vector_type(2)));
;         const u32x2_t yb = __builtin_nontemporal_load((const u32x2_t*)(y + (size_t)row * DM + 4 * lane + 256 * i));
;         yv[i] = f32x4{bflo(yb.x), bfhi(yb.x), bflo(yb.y), bfhi(yb.y)};
;         ss += yv[i][0] * yv[i][0] + yv[i][1] * yv[i][1] + yv[i][2] * yv[i][2] + yv[i][3] * yv[i][3];
;       }
;       ss = wave_sum(ss);
;       float r = c * rsqrtf(ss * (1.f / DM) + EPS);
; #pragma unroll
;       for (int i = 0; i < 4; ++i) {
;         f32x4 g = *(const f32x4*)(g_post + 4 * lane + 256 * i);
;         xv[i] += yv[i] * g * r;
.LBB0_705:
	v_ashrrev_i32_e32 v33, 31, v32
	v_lshlrev_b64 v[40:41], 11, v[32:33]
	v_lshl_add_u64 v[40:41], v[36:37], 0, v[40:41]
	global_load_dwordx2 v[60:61], v[40:41], off offset:512
	global_load_dwordx2 v[62:63], v[40:41], off
	global_load_dwordx2 v[64:65], v[40:41], off offset:1536
	global_load_dwordx2 v[66:67], v[40:41], off offset:1024
	v_lshlrev_b64 v[40:41], 12, v[32:33]
	v_lshl_add_u64 v[40:41], v[34:35], 0, v[40:41]
	global_load_dwordx4 v[44:47], v[40:41], off nt
	global_load_dwordx4 v[48:51], v[40:41], off offset:1024 nt
	global_load_dwordx4 v[52:55], v[40:41], off offset:2048 nt
	global_load_dwordx4 v[56:59], v[40:41], off offset:3072 nt
	s_waitcnt vmcnt(7)
	v_and_b32_e32 v71, 0xffff0000, v60
	s_waitcnt vmcnt(6)
	v_and_b32_e32 v70, 0xffff0000, v62
	v_lshlrev_b32_e32 v69, 16, v60
	v_lshlrev_b32_e32 v68, 16, v62
	v_lshlrev_b32_e32 v72, 16, v63
	v_and_b32_e32 v60, 0xffff0000, v63
	s_waitcnt vmcnt(5)
	v_lshlrev_b32_e32 v63, 16, v64
	s_waitcnt vmcnt(4)
	v_lshlrev_b32_e32 v62, 16, v66
	v_and_b32_e32 v75, 0xffff0000, v64
	v_and_b32_e32 v74, 0xffff0000, v66
	v_lshlrev_b32_e32 v76, 16, v67
	v_and_b32_e32 v64, 0xffff0000, v67
	v_pk_mul_f32 v[66:67], v[70:71], v[70:71]
	v_lshlrev_b32_e32 v73, 16, v61
	v_pk_mul_f32 v[78:79], v[74:75], v[74:75]
	v_pk_fma_f32 v[66:67], v[68:69], v[68:69], v[66:67]
	v_and_b32_e32 v61, 0xffff0000, v61
	v_lshlrev_b32_e32 v77, 16, v65
	v_pk_fma_f32 v[78:79], v[62:63], v[62:63], v[78:79]
	v_pk_fma_f32 v[66:67], v[72:73], v[72:73], v[66:67]
	v_and_b32_e32 v65, 0xffff0000, v65
	v_pk_fma_f32 v[78:79], v[76:77], v[76:77], v[78:79]
	v_pk_fma_f32 v[66:67], v[60:61], v[60:61], v[66:67]
	v_pk_fma_f32 v[78:79], v[64:65], v[64:65], v[78:79]
	v_add_f32_e32 v33, v66, v67
	v_add_f32_e32 v33, v33, v78
	v_add_f32_e32 v33, v33, v79
	ds_bpermute_b32 v43, v159, v33
	v_mov_b32_e32 v66, v68
	v_mov_b32_e32 v67, v70
	v_mov_b32_e32 v70, v69
	v_mov_b32_e32 v78, v72
	s_waitcnt lgkmcnt(0)
	v_add_f32_e32 v33, v33, v43
	ds_bpermute_b32 v43, v160, v33
	v_mov_b32_e32 v68, v62
	v_mov_b32_e32 v69, v74
	v_mov_b32_e32 v74, v63
	v_pk_mul_f32 v[62:63], v[8:9], v[66:67]
	s_waitcnt lgkmcnt(0)
	v_add_f32_e32 v33, v33, v43
	ds_bpermute_b32 v43, v161, v33
	v_pk_mul_f32 v[70:71], v[0:1], v[70:71]
	v_mov_b32_e32 v79, v60
	v_pk_mul_f32 v[68:69], v[4:5], v[68:69]
	v_pk_mul_f32 v[74:75], v[16:17], v[74:75]
	s_waitcnt lgkmcnt(0)
	v_add_f32_e32 v33, v33, v43
	ds_bpermute_b32 v43, v162, v33
	v_mov_b32_e32 v60, v73
	v_mov_b32_e32 v80, v76
	v_mov_b32_e32 v81, v64
	v_pk_mul_f32 v[66:67], v[10:11], v[78:79]
	s_waitcnt lgkmcnt(0)
	v_add_f32_e32 v33, v33, v43
	ds_bpermute_b32 v43, v163, v33
	v_mov_b32_e32 v64, v77
	v_pk_mul_f32 v[60:61], v[2:3], v[60:61]
	v_pk_mul_f32 v[78:79], v[6:7], v[80:81]
	v_pk_mul_f32 v[64:65], v[18:19], v[64:65]
	s_waitcnt lgkmcnt(0)
	v_add_f32_e32 v33, v33, v43
	ds_bpermute_b32 v43, v164, v33
	s_waitcnt lgkmcnt(0)
	v_add_f32_e32 v33, v33, v43
	v_fmamk_f32 v33, v33, 0x3a800000, v42
	v_mul_f32_e32 v43, 0x4b800000, v33
	v_cmp_gt_f32_e32 vcc, s5, v33
	s_nop 1
	v_cndmask_b32_e32 v33, v33, v43, vcc
	v_rsq_f32_e32 v33, v33
	s_nop 0
	v_mul_f32_e32 v43, 0x45800000, v33
	v_cndmask_b32_e32 v72, v33, v43, vcc
	s_waitcnt vmcnt(3)
	v_pk_fma_f32 v[44:45], v[62:63], v[72:73], v[44:45] op_sel_hi:[1,0,1]
	s_waitcnt vmcnt(2)
	v_pk_fma_f32 v[48:49], v[70:71], v[72:73], v[48:49] op_sel_hi:[1,0,1]
	s_waitcnt vmcnt(1)
	v_pk_fma_f32 v[52:53], v[68:69], v[72:73], v[52:53] op_sel_hi:[1,0,1]
	s_waitcnt vmcnt(0)
; DI void row_phase(const float* __restrict__ x_in, const u16* __restrict__ y, float c, const float* __restrict__ g_post,
;                   float* __restrict__ x_out, const float* __restrict__ g_pre, u16* __restrict__ hout) {
;     ...
;       ss = wave_sum(ss);
;       float r = c * rsqrtf(ss * (1.f / DM) + EPS);
; #pragma unroll
;       for (int i = 0; i < 4; ++i) {
;         f32x4 g = *(const f32x4*)(g_post + 4 * lane + 256 * i);
;         xv[i] += yv[i] * g * r;
;         __builtin_nontemporal_store(xv[i], (f32x4*)(x_out + (size_t)row * DM + 4 * lane + 256 * i));
;       }
;     }
;     if (g_pre) {
;       float ss = 0.f;
; #pragma unroll
;       for (int i = 0; i < 4; ++i) ss += xv[i][0] * xv[i][0] + xv[i][1] * xv[i][1] + xv[i][2] * xv[i][2] + xv[i][3] * xv[i][3];
;       ss = wave_sum(ss);
;       float r = rsqrtf(ss * (1.f / DM) + EPS);
; #pragma unroll
;       for (int i = 0; i < 4; ++i) {
;         f32x4 g = *(const f32x4*)(g_pre + 4 * lane + 256 * i);
;         f32x4 hv = xv[i] * g * r;
;         uint2 o = {pack2(hv[0], hv[1]), pack2(hv[2], hv[3])};
;         *(uint2*)(hout + (size_t)row * LDH + 4 * lane + 256 * i) = o;
;       }
	v_pk_fma_f32 v[56:57], v[74:75], v[72:73], v[56:57] op_sel_hi:[1,0,1]
	v_mov_b32_e32 v62, v45
	v_mov_b32_e32 v63, v49
	v_pk_fma_f32 v[46:47], v[66:67], v[72:73], v[46:47] op_sel_hi:[1,0,1]
	v_pk_fma_f32 v[50:51], v[60:61], v[72:73], v[50:51] op_sel_hi:[1,0,1]
	v_mov_b32_e32 v60, v44
	v_mov_b32_e32 v61, v48
	v_mov_b32_e32 v70, v57
	v_mov_b32_e32 v71, v53
	v_pk_mul_f32 v[62:63], v[62:63], v[62:63]
	v_pk_fma_f32 v[54:55], v[78:79], v[72:73], v[54:55] op_sel_hi:[1,0,1]
	v_pk_fma_f32 v[58:59], v[64:65], v[72:73], v[58:59] op_sel_hi:[1,0,1]
	v_mov_b32_e32 v64, v46
	v_mov_b32_e32 v65, v50
	v_mov_b32_e32 v68, v56
	v_mov_b32_e32 v69, v52
	v_pk_mul_f32 v[70:71], v[70:71], v[70:71]
	v_pk_fma_f32 v[60:61], v[60:61], v[60:61], v[62:63]
	v_mov_b32_e32 v66, v47
	v_mov_b32_e32 v67, v51
	v_mov_b32_e32 v72, v58
	v_mov_b32_e32 v73, v54
	v_pk_fma_f32 v[62:63], v[68:69], v[68:69], v[70:71]
	v_pk_fma_f32 v[60:61], v[64:65], v[64:65], v[60:61]
	v_mov_b32_e32 v74, v59
	v_mov_b32_e32 v75, v55
	v_pk_fma_f32 v[62:63], v[72:73], v[72:73], v[62:63]
	v_pk_fma_f32 v[60:61], v[66:67], v[66:67], v[60:61]
	v_pk_fma_f32 v[62:63], v[74:75], v[74:75], v[62:63]
	v_add_f32_e32 v33, v60, v61
	v_add_f32_e32 v33, v63, v33
	v_add_f32_e32 v33, v62, v33
	ds_bpermute_b32 v43, v159, v33
	v_mad_i64_i32 v[60:61], s[16:17], v32, s6, v[38:39]
	v_add_u32_e32 v32, s4, v32
	v_cmp_lt_i32_e32 vcc, s7, v32
	s_waitcnt lgkmcnt(0)
	v_add_f32_e32 v33, v33, v43
	ds_bpermute_b32 v43, v160, v33
	s_or_b64 s[2:3], vcc, s[2:3]
	global_store_dwordx4 v[40:41], v[44:47], off nt
	global_store_dwordx4 v[40:41], v[48:51], off offset:1024 nt
	global_store_dwordx4 v[40:41], v[52:55], off offset:2048 nt
	global_store_dwordx4 v[40:41], v[56:59], off offset:3072 nt
	v_pk_mul_f32 v[40:41], v[12:13], v[44:45]
	s_waitcnt lgkmcnt(0)
	v_add_f32_e32 v33, v33, v43
	ds_bpermute_b32 v43, v161, v33
	v_pk_mul_f32 v[44:45], v[14:15], v[46:47]
	v_pk_mul_f32 v[46:47], v[20:21], v[48:49]
	v_pk_mul_f32 v[48:49], v[22:23], v[50:51]
	v_pk_mul_f32 v[50:51], v[24:25], v[52:53]
	s_waitcnt lgkmcnt(0)
	v_add_f32_e32 v33, v33, v43
	ds_bpermute_b32 v43, v162, v33
	v_pk_mul_f32 v[52:53], v[26:27], v[54:55]
	v_pk_mul_f32 v[54:55], v[28:29], v[56:57]
	v_pk_mul_f32 v[56:57], v[30:31], v[58:59]
	s_waitcnt lgkmcnt(0)
	v_add_f32_e32 v33, v33, v43
	ds_bpermute_b32 v43, v163, v33
	s_waitcnt lgkmcnt(0)
	v_add_f32_e32 v33, v33, v43
	ds_bpermute_b32 v43, v164, v33
	s_waitcnt lgkmcnt(0)
	v_add_f32_e32 v33, v33, v43
	v_fmamk_f32 v33, v33, 0x3a800000, v42
	v_mul_f32_e32 v43, 0x4b800000, v33
	v_cmp_gt_f32_e32 vcc, s5, v33
	s_nop 1
	v_cndmask_b32_e32 v33, v33, v43, vcc
	v_rsq_f32_e32 v33, v33
	s_nop 0
	v_mul_f32_e32 v43, 0x45800000, v33
	v_cndmask_b32_e32 v58, v33, v43, vcc
	v_pk_mul_f32 v[44:45], v[44:45], v[58:59] op_sel_hi:[1,0]
	v_pk_mul_f32 v[40:41], v[40:41], v[58:59] op_sel_hi:[1,0]
	v_pk_mul_f32 v[48:49], v[48:49], v[58:59] op_sel_hi:[1,0]
	v_pk_mul_f32 v[46:47], v[46:47], v[58:59] op_sel_hi:[1,0]
	v_pk_mul_f32 v[52:53], v[52:53], v[58:59] op_sel_hi:[1,0]
	v_pk_mul_f32 v[50:51], v[50:51], v[58:59] op_sel_hi:[1,0]
	v_pk_mul_f32 v[56:57], v[56:57], v[58:59] op_sel_hi:[1,0]
	v_pk_mul_f32 v[54:55], v[54:55], v[58:59] op_sel_hi:[1,0]
	v_cvt_pk_bf16_f32 v40, v40, v41
	v_cvt_pk_bf16_f32 v41, v44, v45
	v_cvt_pk_bf16_f32 v44, v46, v47
	v_cvt_pk_bf16_f32 v45, v48, v49
	v_cvt_pk_bf16_f32 v46, v50, v51
	v_cvt_pk_bf16_f32 v47, v52, v53
	v_cvt_pk_bf16_f32 v48, v54, v55
	v_cvt_pk_bf16_f32 v49, v56, v57
	global_store_dwordx2 v[60:61], v[40:41], off
	global_store_dwordx2 v[60:61], v[44:45], off offset:512
	global_store_dwordx2 v[60:61], v[46:47], off offset:1024
	global_store_dwordx2 v[60:61], v[48:49], off offset:1536
	s_andn2_b64 exec, exec, s[2:3]
	s_cbranch_execnz .LBB0_705

; DI float bflo(unsigned u) { return __uint_as_float(u << 16); }
; DI float bfhi(unsigned u) { return __uint_as_float(u & 0xffff0000u); }
; DI int lbid() { int b = blockIdx.x; asm volatile("" : "+s"(b)); return b; }
; DI void row_phase(const float* __restrict__ x_in, const u16* __restrict__ y, float c, const float* __restrict__ g_post,
;                   float* __restrict__ x_out, const float* __restrict__ g_pre, u16* __restrict__ hout) {
;     ...
;   for (int row = lbid() * 8 + wid; row < S; row += gridDim.x * 8) {
;     f32x4 xv[4];
; #pragma unroll
;     for (int i = 0; i < 4; ++i) xv[i] = __builtin_nontemporal_load((const f32x4*)(x_in + (size_t)row * DM + 4 * lane + 256 * i));
;     if (y) {
;       f32x4 yv[4];
;       float ss = 0.f;
; #pragma unroll
;       for (int i = 0; i < 4; ++i) {
;         typedef unsigned u32x2_t __attribute__((ext_vector_type(2)));
;         const u32x2_t yb = __builtin_nontemporal_load((const u32x2_t*)(y + (size_t)row * DM + 4 * lane + 256 * i));
;         yv[i] = f32x4{bflo(yb.x), bfhi(yb.x), bflo(yb.y), bfhi(yb.y)};
;         ss += yv[i][0] * yv[i][0] + yv[i][1] * yv[i][1] + yv[i][2] * yv[i][2] + yv[i][3] * yv[i][3];
;       }
;       ss = wave_sum(ss);
;       float r = c * rsqrtf(ss * (1.f / DM) + EPS);
; #pragma unroll
;       for (int i = 0; i < 4; ++i) {
;         f32x4 g = *(const f32x4*)(g_post + 4 * lane + 256 * i);
;         xv[i] += yv[i] * g * r;
;         __builtin_nontemporal_store(xv[i], (f32x4*)(x_out + (size_t)row * DM + 4 * lane + 256 * i));
;       }
.LBB0_778:
	v_ashrrev_i32_e32 v17, 31, v16
	v_lshlrev_b64 v[24:25], 11, v[16:17]
	v_lshl_add_u64 v[24:25], v[20:21], 0, v[24:25]
	global_load_dwordx2 v[40:41], v[24:25], off offset:512
	global_load_dwordx2 v[42:43], v[24:25], off
	global_load_dwordx2 v[44:45], v[24:25], off offset:1536
	global_load_dwordx2 v[46:47], v[24:25], off offset:1024
	v_lshlrev_b64 v[24:25], 12, v[16:17]
	v_lshl_add_u64 v[48:49], v[18:19], 0, v[24:25]
	global_load_dwordx4 v[24:27], v[48:49], off nt
	global_load_dwordx4 v[28:31], v[48:49], off offset:1024 nt
	global_load_dwordx4 v[32:35], v[48:49], off offset:2048 nt
	global_load_dwordx4 v[36:39], v[48:49], off offset:3072 nt
	v_add_u32_e32 v16, s2, v16
	v_cmp_lt_i32_e32 vcc, s4, v16
	s_or_b64 s[0:1], vcc, s[0:1]
	s_waitcnt vmcnt(7)
	v_and_b32_e32 v53, 0xffff0000, v40
	s_waitcnt vmcnt(6)
	v_and_b32_e32 v52, 0xffff0000, v42
	v_lshlrev_b32_e32 v51, 16, v40
	v_lshlrev_b32_e32 v50, 16, v42
	v_lshlrev_b32_e32 v54, 16, v43
	v_and_b32_e32 v40, 0xffff0000, v43
	s_waitcnt vmcnt(5)
	v_lshlrev_b32_e32 v43, 16, v44
	s_waitcnt vmcnt(4)
	v_lshlrev_b32_e32 v42, 16, v46
	v_and_b32_e32 v57, 0xffff0000, v44
	v_and_b32_e32 v56, 0xffff0000, v46
	v_lshlrev_b32_e32 v58, 16, v47
	v_and_b32_e32 v44, 0xffff0000, v47
	v_pk_mul_f32 v[46:47], v[52:53], v[52:53]
	v_lshlrev_b32_e32 v55, 16, v41
	v_pk_mul_f32 v[60:61], v[56:57], v[56:57]
	v_pk_fma_f32 v[46:47], v[50:51], v[50:51], v[46:47]
	v_and_b32_e32 v41, 0xffff0000, v41
	v_lshlrev_b32_e32 v59, 16, v45
	v_pk_fma_f32 v[60:61], v[42:43], v[42:43], v[60:61]
	v_pk_fma_f32 v[46:47], v[54:55], v[54:55], v[46:47]
	v_and_b32_e32 v45, 0xffff0000, v45
	v_pk_fma_f32 v[60:61], v[58:59], v[58:59], v[60:61]
	v_pk_fma_f32 v[46:47], v[40:41], v[40:41], v[46:47]
	v_pk_fma_f32 v[60:61], v[44:45], v[44:45], v[60:61]
	v_add_f32_e32 v17, v46, v47
	v_add_f32_e32 v17, v17, v60
	v_add_f32_e32 v17, v17, v61
	ds_bpermute_b32 v23, v159, v17
	v_mov_b32_e32 v46, v50
	v_mov_b32_e32 v47, v52
	v_mov_b32_e32 v60, v54
	v_mov_b32_e32 v61, v40
	s_waitcnt lgkmcnt(0)
	v_add_f32_e32 v17, v17, v23
	ds_bpermute_b32 v23, v160, v17
	v_mov_b32_e32 v52, v51
	v_mov_b32_e32 v50, v42
	v_mov_b32_e32 v51, v56
	v_mov_b32_e32 v62, v58
	s_waitcnt lgkmcnt(0)
	v_add_f32_e32 v17, v17, v23
	ds_bpermute_b32 v23, v161, v17
	v_mov_b32_e32 v63, v44
	v_mov_b32_e32 v56, v43
	v_pk_mul_f32 v[42:43], v[8:9], v[46:47]
	v_pk_mul_f32 v[46:47], v[10:11], v[60:61]
	s_waitcnt lgkmcnt(0)
	v_add_f32_e32 v17, v17, v23
	ds_bpermute_b32 v23, v162, v17
	v_mov_b32_e32 v40, v55
	v_mov_b32_e32 v44, v59
	v_pk_mul_f32 v[52:53], v[0:1], v[52:53]
	v_pk_mul_f32 v[50:51], v[4:5], v[50:51]
	s_waitcnt lgkmcnt(0)
	v_add_f32_e32 v17, v17, v23
	ds_bpermute_b32 v23, v163, v17
	v_pk_mul_f32 v[60:61], v[6:7], v[62:63]
	v_pk_mul_f32 v[56:57], v[12:13], v[56:57]
	v_pk_mul_f32 v[40:41], v[2:3], v[40:41]
	v_pk_mul_f32 v[44:45], v[14:15], v[44:45]
	s_waitcnt lgkmcnt(0)
	v_add_f32_e32 v17, v17, v23
	ds_bpermute_b32 v23, v164, v17
	s_waitcnt lgkmcnt(0)
	v_add_f32_e32 v17, v17, v23
	v_fmamk_f32 v17, v17, 0x3a800000, v22
	v_mul_f32_e32 v23, 0x4b800000, v17
	v_cmp_gt_f32_e32 vcc, s3, v17
	s_nop 1
	v_cndmask_b32_e32 v17, v17, v23, vcc
	v_rsq_f32_e32 v17, v17
	s_nop 0
	v_mul_f32_e32 v23, 0x45800000, v17
	v_cndmask_b32_e32 v17, v17, v23, vcc
	v_mul_f32_e32 v54, 0.5, v17
	s_waitcnt vmcnt(3)
	v_pk_fma_f32 v[26:27], v[46:47], v[54:55], v[26:27] op_sel_hi:[1,0,1]
	v_pk_fma_f32 v[24:25], v[42:43], v[54:55], v[24:25] op_sel_hi:[1,0,1]
	s_waitcnt vmcnt(2)
	v_pk_fma_f32 v[30:31], v[40:41], v[54:55], v[30:31] op_sel_hi:[1,0,1]
	v_pk_fma_f32 v[28:29], v[52:53], v[54:55], v[28:29] op_sel_hi:[1,0,1]
	s_waitcnt vmcnt(1)
	v_pk_fma_f32 v[34:35], v[60:61], v[54:55], v[34:35] op_sel_hi:[1,0,1]
	v_pk_fma_f32 v[32:33], v[50:51], v[54:55], v[32:33] op_sel_hi:[1,0,1]
	s_waitcnt vmcnt(0)
	v_pk_fma_f32 v[38:39], v[44:45], v[54:55], v[38:39] op_sel_hi:[1,0,1]
	v_pk_fma_f32 v[36:37], v[56:57], v[54:55], v[36:37] op_sel_hi:[1,0,1]
	global_store_dwordx4 v[48:49], v[24:27], off nt
	global_store_dwordx4 v[48:49], v[28:31], off offset:1024 nt
	global_store_dwordx4 v[48:49], v[32:35], off offset:2048 nt
	global_store_dwordx4 v[48:49], v[36:39], off offset:3072 nt
	s_andn2_b64 exec, exec, s[0:1]
	s_cbranch_execnz .LBB0_778
